# attention MODE0 steady loop: selection mask folded into the QK C-init block via one rank-1 bf16 MFMA per step (replaces 17 v_and per step); reference max rounded to bf16-exact at loop entry with exact
# speedup vs baseline: 1.0153x; 1.0153x over previous
.LBB0_796:
	v_lshlrev_b32_e32 v53, 1, v52
	v_lshlrev_b32_e32 v52, 4, v52
	v_and_b32_e32 v214, 32, v53
	v_and_b32_e32 v52, 0xc0, v52
	v_lshl_or_b32 v213, v209, 8, v52
	v_add_u32_e32 v52, 0, v214
	v_add3_u32 v219, v52, v211, v213
	v_max3_f32 v52, v36, v37, v20
	v_max3_f32 v53, v38, v39, v21
	s_and_b32 s0, s22, 0x3fffffc0
	v_max3_f32 v52, v52, v22, v23
	v_max3_f32 v53, v53, v42, v43
	s_lshl_b32 s0, s0, 2
	v_max3_f32 v52, v52, v40, v41
	v_max3_f32 v53, v53, v26, v27
	s_add_i32 s1, s64, 0x100
	v_max3_f32 v52, v52, v24, v25
	v_max3_f32 v53, v53, v46, v47
	s_add_i32 s53, s0, 0
	v_max3_f32 v52, v52, v44, v45
	v_max3_f32 v53, v53, v30, v31
	s_lshr_b32 s48, s1, 6
	v_max3_f32 v52, v52, v28, v29
	v_max3_f32 v53, v53, v50, v51
	s_mov_b64 s[22:23], 0x60000
	v_max3_f32 v52, v52, v48, v49
	v_max3_f32 v53, v53, v34, v35
	s_cmp_lg_u32 0, -1
	v_max3_f32 v52, v52, v32, v33
	s_mov_b64 s[10:11], 0x20000
	v_max_f32_e32 v52, v52, v53
	v_lshl_add_u64 v[190:191], v[84:85], 0, s[10:11]
	v_mov_b32_e32 v53, v52
	s_nop 1
	v_permlane32_swap_b32_e32 v52, v53
	v_max_f32_e32 v52, v52, v53
	s_mov_b32 s0, 1
	v_max_f32_e32 v52, v52, v228
	s_mov_b32 s24, 0
	v_add_f32_e32 v217, v3, v52
	v_sub_f32_e32 v53, v36, v52
	v_sub_f32_e32 v54, v37, v52
	v_sub_f32_e32 v55, v38, v52
	v_sub_f32_e32 v56, v39, v52
	v_sub_f32_e32 v57, v40, v52
	s_nop 0
	v_xor_b32_e32 v36, 0x80000000, v217
	v_sub_f32_e32 v58, v41, v52
	v_sub_f32_e32 v59, v42, v52
	v_sub_f32_e32 v60, v43, v52
	v_sub_f32_e32 v61, v44, v52
	v_sub_f32_e32 v62, v45, v52
	v_sub_f32_e32 v63, v46, v52
	v_sub_f32_e32 v64, v47, v52
	v_sub_f32_e32 v65, v48, v52
	v_sub_f32_e32 v66, v49, v52
	v_sub_f32_e32 v67, v50, v52
	v_sub_f32_e32 v83, v51, v52
	v_mov_b32_e32 v37, v36
	v_mov_b32_e32 v38, v36
	v_mov_b32_e32 v39, v36
	v_mov_b32_e32 v40, v36
	v_mov_b32_e32 v41, v36
	v_mov_b32_e32 v42, v36
	v_mov_b32_e32 v43, v36
	v_mov_b32_e32 v44, v36
	v_mov_b32_e32 v45, v36
	v_mov_b32_e32 v46, v36
	v_mov_b32_e32 v47, v36
	v_mov_b32_e32 v48, v36
	v_mov_b32_e32 v49, v36
	v_mov_b32_e32 v50, v36
	v_mov_b32_e32 v51, v36
	v_sub_f32_e32 v20, v20, v52
	v_sub_f32_e32 v21, v21, v52
	s_waitcnt vmcnt(0) lgkmcnt(0)
	s_barrier
	v_sub_f32_e32 v22, v22, v52
	v_sub_f32_e32 v23, v23, v52
	v_sub_f32_e32 v24, v24, v52
	v_sub_f32_e32 v25, v25, v52
	v_sub_f32_e32 v26, v26, v52
	v_sub_f32_e32 v27, v27, v52
	v_sub_f32_e32 v28, v28, v52
	v_sub_f32_e32 v29, v29, v52
	v_sub_f32_e32 v30, v30, v52
	v_sub_f32_e32 v31, v31, v52
	v_sub_f32_e32 v32, v32, v52
	v_sub_f32_e32 v33, v33, v52
	v_sub_f32_e32 v34, v34, v52
	v_sub_f32_e32 v35, v35, v52
	v_exp_f32_e32 v68, v53
	v_exp_f32_e32 v52, v20
	v_exp_f32_e32 v53, v21
	v_lshl_add_u64 v[20:21], v[188:189], 0, s[22:23]
	s_mov_b32 m0, s46
	s_nop 0
	global_load_lds_dwordx4 v[20:21], off
	s_cselect_b32 s1, 0, 0
	s_add_i32 s1, s1, s45
	s_add_i32 s1, s1, 0x8000
	s_mov_b32 m0, s1
	s_nop 0
	global_load_lds_dwordx4 v[190:191], off
	ds_read_b128 v[180:183], v218 offset:8192
	ds_read_b128 v[176:179], v218 offset:8704
	ds_read_b128 v[172:175], v218 offset:10240
	ds_read_b128 v[168:171], v218 offset:10752
	ds_read_b128 v[164:167], v218 offset:12288
	ds_read_b128 v[160:163], v218 offset:12800
	ds_read_b128 v[156:159], v218 offset:14336
	ds_read_b128 v[152:155], v218 offset:14848
	v_exp_f32_e32 v69, v54
	v_exp_f32_e32 v70, v55
	v_exp_f32_e32 v71, v56
	v_exp_f32_e32 v72, v57
	v_exp_f32_e32 v73, v58
	v_exp_f32_e32 v74, v59
	v_exp_f32_e32 v75, v60
	v_exp_f32_e32 v76, v61
	v_exp_f32_e32 v77, v62
	v_exp_f32_e32 v78, v63
	v_exp_f32_e32 v79, v64
	v_exp_f32_e32 v80, v65
	v_exp_f32_e32 v81, v66
	v_exp_f32_e32 v82, v67
	v_exp_f32_e32 v83, v83
	v_exp_f32_e32 v54, v22
	v_exp_f32_e32 v55, v23
	v_exp_f32_e32 v56, v24
	v_exp_f32_e32 v57, v25
	v_exp_f32_e32 v58, v26
	v_exp_f32_e32 v59, v27
	v_exp_f32_e32 v60, v28
	v_exp_f32_e32 v61, v29
	v_exp_f32_e32 v62, v30
	v_exp_f32_e32 v63, v31
	v_exp_f32_e32 v64, v32
	v_exp_f32_e32 v65, v33
	v_exp_f32_e32 v66, v34
	v_exp_f32_e32 v67, v35
	s_waitcnt vmcnt(2) lgkmcnt(0)
	s_barrier
	s_andn2_b64 vcc, exec, s[4:5]
	v_cmp_gt_u32_e64 s[4:5], 32, v1
	s_cbranch_vccnz .LBB0_812
	v_lshlrev_b32_e32 v20, 4, v209
	s_mov_b64 s[10:11], 0xa0000
	v_add_u32_e32 v203, s53, v20
	v_mov_b64_e32 v[34:35], v[18:19]
	s_add_i32 s1, s48, -5
	v_lshl_add_u32 v202, v208, 2, s53
	v_lshl_add_u64 v[192:193], v[84:85], 0, s[22:23]
	v_lshl_add_u64 v[194:195], v[188:189], 0, s[10:11]
	s_movk_i32 s24, 0x4000
	s_movk_i32 s25, 0x2000
	s_mov_b32 s10, 0
	v_mov_b32_e32 v220, 0
	v_mov_b64_e32 v[32:33], v[16:17]
	v_mov_b64_e32 v[30:31], v[14:15]
	v_mov_b64_e32 v[28:29], v[12:13]
	v_mov_b64_e32 v[26:27], v[10:11]
	v_mov_b64_e32 v[24:25], v[8:9]
	v_mov_b64_e32 v[22:23], v[6:7]
	v_mov_b64_e32 v[20:21], v[4:5]
	s_mov_b64 s[98:99], exec
	v_and_b32_e32 v224, 0xffff0000, v36
	v_sub_f32_e32 v225, v224, v36
	v_exp_f32_e32 v225, v225
	v_bfe_i32 v196, v132, 0, 1
	v_mov_b32_e32 v250, 0
	v_mov_b32_e32 v251, 0
	v_mov_b32_e32 v252, 0
	v_mov_b32_e32 v253, 0
	v_mov_b32_e32 v247, 0
	v_mov_b32_e32 v248, 0
	v_mov_b32_e32 v249, 0
	v_mov_b32_e32 v222, 0
	v_mov_b32_e32 v223, 0
	s_mov_b32 exec_hi, 0
	v_mov_b32_e32 v250, 0x3f80
	v_mov_b32_e32 v223, 0xf180
	v_lshrrev_b32_e32 v222, 16, v224
	s_mov_b64 exec, s[98:99]
	v_and_b32_e32 v224, v225, v196
	v_mul_f32_e32 v4, v225, v4
	v_mul_f32_e32 v5, v225, v5
	v_mul_f32_e32 v6, v225, v6
	v_mul_f32_e32 v7, v225, v7
	v_mul_f32_e32 v8, v225, v8
	v_mul_f32_e32 v9, v225, v9
	v_mul_f32_e32 v10, v225, v10
	v_mul_f32_e32 v11, v225, v11
	v_mul_f32_e32 v12, v225, v12
	v_mul_f32_e32 v13, v225, v13
	v_mul_f32_e32 v14, v225, v14
	v_mul_f32_e32 v15, v225, v15
	v_mul_f32_e32 v16, v225, v16
	v_mul_f32_e32 v17, v225, v17
	v_mul_f32_e32 v18, v225, v18
	v_mul_f32_e32 v19, v225, v19
	v_mul_f32_e32 v20, v225, v20
	v_mul_f32_e32 v21, v225, v21
	v_mul_f32_e32 v22, v225, v22
	v_mul_f32_e32 v23, v225, v23
	v_mul_f32_e32 v24, v225, v24
	v_mul_f32_e32 v25, v225, v25
	v_mul_f32_e32 v26, v225, v26
	v_mul_f32_e32 v27, v225, v27
	v_mul_f32_e32 v28, v225, v28
	v_mul_f32_e32 v29, v225, v29
	v_mul_f32_e32 v30, v225, v30
	v_mul_f32_e32 v31, v225, v31
	v_mul_f32_e32 v32, v225, v32
	v_mul_f32_e32 v33, v225, v33
	v_mul_f32_e32 v34, v225, v34
	v_mul_f32_e32 v35, v225, v35
	v_mul_f32_e32 v52, v224, v52
	v_mul_f32_e32 v53, v224, v53
	v_mul_f32_e32 v54, v224, v54
	v_mul_f32_e32 v55, v224, v55
	v_mul_f32_e32 v56, v224, v56
	v_mul_f32_e32 v57, v224, v57
	v_mul_f32_e32 v58, v224, v58
	v_mul_f32_e32 v59, v224, v59
	v_mul_f32_e32 v60, v224, v60
	v_mul_f32_e32 v61, v224, v61
	v_mul_f32_e32 v62, v224, v62
	v_mul_f32_e32 v63, v224, v63
	v_mul_f32_e32 v64, v224, v64
	v_mul_f32_e32 v65, v224, v65
	v_mul_f32_e32 v66, v224, v66
	v_mul_f32_e32 v67, v224, v67
	v_mul_f32_e32 v68, v224, v68
	v_mul_f32_e32 v69, v224, v69
	v_mul_f32_e32 v70, v224, v70
	v_mul_f32_e32 v71, v224, v71
	v_mul_f32_e32 v72, v224, v72
	v_mul_f32_e32 v73, v224, v73
	v_mul_f32_e32 v74, v224, v74
	v_mul_f32_e32 v75, v224, v75
	v_mul_f32_e32 v76, v224, v76
	v_mul_f32_e32 v77, v224, v77
	v_mul_f32_e32 v78, v224, v78
	v_mul_f32_e32 v79, v224, v79
	v_mul_f32_e32 v80, v224, v80
	v_mul_f32_e32 v81, v224, v81
	v_mul_f32_e32 v82, v224, v82
	v_mul_f32_e32 v83, v224, v83
	v_mul_f32_e32 v220, v225, v220
	v_bfe_i32 v196, v132, 1, 1
	v_bfi_b32 v246, v196, v222, v223
	s_mov_b32 s101, 2
	s_nop 1
	v_mfma_f32_32x32x16_bf16 v[36:51], v[250:253], v[246:249], 0
	s_branch .LBB0_798

.LBB0_798:
	v_add_u32_e32 v197, s10, v219
	ds_read_b64_tr_b16 v[184:185], v197 offset:24576
	ds_read_b64_tr_b16 v[186:187], v197 offset:25088
	v_mfma_f32_32x32x16_bf16 v[100:115], v[180:183], v[116:119], v[36:51]
	v_add_f32_e32 v84, v68, v69
	v_add_f32_e32 v84, v70, v84
	v_add_f32_e32 v84, v71, v84
	v_cvt_pk_bf16_f32 v148, v68, v69
	v_add_f32_e32 v84, v72, v84
	v_cvt_pk_bf16_f32 v149, v70, v71
	v_add_f32_e32 v84, v73, v84
	ds_read_b64_tr_b16 v[180:181], v197 offset:28672
	ds_read_b64_tr_b16 v[182:183], v197 offset:29184
	v_add_f32_e32 v68, v74, v84
	v_mfma_f32_32x32x16_bf16 v[84:99], v[176:179], v[116:119], v[36:51]
	v_add_f32_e32 v68, v75, v68
	v_add_f32_e32 v68, v76, v68
	v_add_f32_e32 v136, v77, v68
	v_cvt_pk_bf16_f32 v150, v72, v73
	v_cvt_pk_bf16_f32 v151, v74, v75
	ds_read_b64_tr_b16 v[68:69], v197 offset:25600
	ds_read_b64_tr_b16 v[70:71], v197 offset:26112
	v_mfma_f32_32x32x16_bf16 v[100:115], v[172:175], v[120:123], v[100:115]
	v_add_f32_e32 v72, v78, v136
	v_add_f32_e32 v72, v79, v72
	v_add_f32_e32 v72, v80, v72
	v_add_f32_e32 v136, v81, v72
	v_cvt_pk_bf16_f32 v144, v76, v77
	v_cvt_pk_bf16_f32 v145, v78, v79
	ds_read_b64_tr_b16 v[72:73], v197 offset:29696
	ds_read_b64_tr_b16 v[74:75], v197 offset:30208
	v_mfma_f32_32x32x16_bf16 v[84:99], v[168:171], v[120:123], v[84:99]
	v_add_f32_e32 v76, v82, v136
	v_add_f32_e32 v76, v83, v76
	v_add_f32_e32 v76, v52, v76
	v_add_f32_e32 v136, v53, v76
	v_cvt_pk_bf16_f32 v146, v80, v81
	v_cvt_pk_bf16_f32 v147, v82, v83
	ds_read_b64_tr_b16 v[76:77], v197 offset:26624
	ds_read_b64_tr_b16 v[78:79], v197 offset:27136
	v_mfma_f32_32x32x16_bf16 v[100:115], v[164:167], v[124:127], v[100:115]
	v_add_f32_e32 v80, v54, v136
	v_add_f32_e32 v80, v55, v80
	v_cvt_pk_bf16_f32 v140, v52, v53
	v_add_f32_e32 v80, v56, v80
	v_cvt_pk_bf16_f32 v141, v54, v55
	v_add_f32_e32 v80, v57, v80
	ds_read_b64_tr_b16 v[52:53], v197 offset:30720
	ds_read_b64_tr_b16 v[54:55], v197 offset:31232
	v_mfma_f32_32x32x16_bf16 v[84:99], v[160:163], v[124:127], v[84:99]
	v_add_f32_e32 v80, v58, v80
	v_add_f32_e32 v80, v59, v80
	v_cvt_pk_bf16_f32 v142, v56, v57
	v_add_f32_e32 v80, v60, v80
	v_cvt_pk_bf16_f32 v143, v58, v59
	v_add_f32_e32 v80, v61, v80
	ds_read_b64_tr_b16 v[56:57], v197 offset:27648
	ds_read_b64_tr_b16 v[58:59], v197 offset:28160
	v_mfma_f32_32x32x16_bf16 v[100:115], v[156:159], v[128:131], v[100:115]
	v_add_f32_e32 v80, v62, v80
	v_add_f32_e32 v80, v63, v80
	v_cvt_pk_bf16_f32 v136, v60, v61
	v_add_f32_e32 v80, v64, v80
	v_cvt_pk_bf16_f32 v137, v62, v63
	v_add_f32_e32 v80, v65, v80
	ds_read_b64_tr_b16 v[60:61], v197 offset:31744
	ds_read_b64_tr_b16 v[62:63], v197 offset:32256
	v_mfma_f32_32x32x16_bf16 v[84:99], v[152:155], v[128:131], v[84:99]
	v_add_f32_e32 v80, v66, v80
	v_cvt_pk_bf16_f32 v138, v64, v65
	v_add_f32_e32 v80, v67, v80
	v_cvt_pk_bf16_f32 v139, v66, v67
	s_mov_b32 s22, 0xfffe0000
	s_mov_b32 s23, -1
	v_lshl_add_u64 v[64:65], v[194:195], 0, s[22:23]
	s_add_i32 s10, s25, s46
	s_mov_b32 m0, s10
	s_nop 0
	global_load_lds_dwordx4 v[64:65], off
	v_lshl_add_u64 v[64:65], v[192:193], 0, s[22:23]
	s_add_i32 s10, s24, s47
	s_mov_b32 m0, s10
	s_nop 0
	global_load_lds_dwordx4 v[64:65], off
	v_add_f32_e32 v204, v220, v80
.LBB0_799:
	s_waitcnt lgkmcnt(14)
	v_mfma_f32_32x32x16_bf16 v[20:35], v[148:151], v[184:187], v[20:35]
	v_exp_f32_e32 v100, v100
	v_exp_f32_e32 v101, v101
	v_exp_f32_e32 v102, v102
	v_exp_f32_e32 v103, v103
	s_waitcnt lgkmcnt(12)
	v_mfma_f32_32x32x16_bf16 v[4:19], v[148:151], v[180:183], v[4:19]
	v_exp_f32_e32 v104, v104
	v_exp_f32_e32 v105, v105
	v_exp_f32_e32 v106, v106
	v_exp_f32_e32 v107, v107
	v_add_u32_e32 v80, s24, v218
	ds_read_b128 v[64:67], v80
	ds_read_b128 v[180:183], v80 offset:512
	s_waitcnt lgkmcnt(12)
	v_mfma_f32_32x32x16_bf16 v[20:35], v[144:147], v[68:71], v[20:35]
	v_exp_f32_e32 v108, v108
	v_exp_f32_e32 v109, v109
	v_exp_f32_e32 v110, v110
	v_exp_f32_e32 v111, v111
	ds_read_b128 v[184:187], v80 offset:2048
	ds_read_b128 v[176:179], v80 offset:2560
	s_waitcnt lgkmcnt(12)
	v_mfma_f32_32x32x16_bf16 v[4:19], v[144:147], v[72:75], v[4:19]
	v_exp_f32_e32 v112, v112
	v_exp_f32_e32 v113, v113
	v_exp_f32_e32 v114, v114
	v_exp_f32_e32 v115, v115
	ds_read_b128 v[172:175], v80 offset:4096
	ds_read_b128 v[168:171], v80 offset:4608
	s_waitcnt lgkmcnt(12)
	v_mfma_f32_32x32x16_bf16 v[20:35], v[140:143], v[76:79], v[20:35]
	v_exp_f32_e32 v84, v84
	v_exp_f32_e32 v85, v85
	v_exp_f32_e32 v86, v86
	v_exp_f32_e32 v87, v87
	ds_read_b128 v[164:167], v80 offset:6144
	ds_read_b128 v[160:163], v80 offset:6656
	s_waitcnt lgkmcnt(12)
	v_mfma_f32_32x32x16_bf16 v[4:19], v[140:143], v[52:55], v[4:19]
	v_exp_f32_e32 v88, v88
	v_exp_f32_e32 v89, v89
	v_exp_f32_e32 v90, v90
	v_exp_f32_e32 v91, v91
	s_waitcnt lgkmcnt(10)
	v_mfma_f32_32x32x16_bf16 v[20:35], v[136:139], v[56:59], v[20:35]
	v_exp_f32_e32 v92, v92
	v_exp_f32_e32 v93, v93
	v_exp_f32_e32 v94, v94
	v_exp_f32_e32 v95, v95
	s_cmp_eq_u32 s101, 32
	s_cbranch_scc1 .Lattn0_rot
.Lattn0_rotback:
	v_bfe_i32 v196, v132, s101, 1
	v_bfi_b32 v246, v196, v222, v223
	s_waitcnt lgkmcnt(8)
	v_mfma_f32_32x32x16_bf16 v[4:19], v[136:139], v[60:63], v[4:19]
	v_exp_f32_e32 v96, v96
	v_exp_f32_e32 v97, v97
	v_exp_f32_e32 v98, v98
	v_exp_f32_e32 v99, v99
	v_mfma_f32_32x32x16_bf16 v[36:51], v[250:253], v[246:249], 0
	s_add_i32 s101, s101, 1
	s_add_i32 s10, s24, 0x2000
	s_cmpk_lg_i32 s24, 0x4000
	s_cselect_b32 s54, s10, 0
	s_waitcnt vmcnt(2) lgkmcnt(0)
	s_barrier
.LBB0_801:
	v_add_u32_e32 v197, s25, v219
	ds_read_b64_tr_b16 v[152:153], v197 offset:24576
	ds_read_b64_tr_b16 v[154:155], v197 offset:25088
	v_mfma_f32_32x32x16_bf16 v[68:83], v[64:67], v[116:119], v[36:51]
	v_add_f32_e32 v52, v100, v101
	v_add_f32_e32 v52, v102, v52
	v_add_f32_e32 v52, v103, v52
	v_cvt_pk_bf16_f32 v148, v100, v101
	v_add_f32_e32 v52, v104, v52
	v_cvt_pk_bf16_f32 v149, v102, v103
	v_add_f32_e32 v52, v105, v52
	ds_read_b64_tr_b16 v[156:157], v197 offset:28672
	ds_read_b64_tr_b16 v[158:159], v197 offset:29184
	v_add_f32_e32 v52, v106, v52
	v_add_f32_e32 v52, v107, v52
	v_add_f32_e32 v52, v108, v52
	v_add_f32_e32 v136, v109, v52
	v_mfma_f32_32x32x16_bf16 v[52:67], v[180:183], v[116:119], v[36:51]
	v_cvt_pk_bf16_f32 v150, v104, v105
	v_cvt_pk_bf16_f32 v151, v106, v107
	ds_read_b64_tr_b16 v[100:101], v197 offset:25600
	ds_read_b64_tr_b16 v[102:103], v197 offset:26112
	v_mfma_f32_32x32x16_bf16 v[68:83], v[184:187], v[120:123], v[68:83]
	v_add_f32_e32 v104, v110, v136
	v_add_f32_e32 v104, v111, v104
	v_add_f32_e32 v104, v112, v104
	v_add_f32_e32 v136, v113, v104
	v_cvt_pk_bf16_f32 v144, v108, v109
	v_cvt_pk_bf16_f32 v145, v110, v111
	ds_read_b64_tr_b16 v[104:105], v197 offset:29696
	ds_read_b64_tr_b16 v[106:107], v197 offset:30208
	v_mfma_f32_32x32x16_bf16 v[52:67], v[176:179], v[120:123], v[52:67]
	v_add_f32_e32 v108, v114, v136
	v_add_f32_e32 v108, v115, v108
	v_add_f32_e32 v108, v84, v108
	v_add_f32_e32 v136, v85, v108
	v_cvt_pk_bf16_f32 v146, v112, v113
	v_cvt_pk_bf16_f32 v147, v114, v115
	ds_read_b64_tr_b16 v[108:109], v197 offset:26624
	ds_read_b64_tr_b16 v[110:111], v197 offset:27136
	v_mfma_f32_32x32x16_bf16 v[68:83], v[172:175], v[124:127], v[68:83]
	v_add_f32_e32 v112, v86, v136
	v_add_f32_e32 v112, v87, v112
	v_cvt_pk_bf16_f32 v140, v84, v85
	v_add_f32_e32 v112, v88, v112
	v_cvt_pk_bf16_f32 v141, v86, v87
	v_add_f32_e32 v112, v89, v112
	ds_read_b64_tr_b16 v[84:85], v197 offset:30720
	ds_read_b64_tr_b16 v[86:87], v197 offset:31232
	v_mfma_f32_32x32x16_bf16 v[52:67], v[168:171], v[124:127], v[52:67]
	v_add_f32_e32 v112, v90, v112
	v_add_f32_e32 v112, v91, v112
	v_cvt_pk_bf16_f32 v142, v88, v89
	v_add_f32_e32 v112, v92, v112
	v_cvt_pk_bf16_f32 v143, v90, v91
	v_add_f32_e32 v112, v93, v112
	ds_read_b64_tr_b16 v[88:89], v197 offset:27648
	ds_read_b64_tr_b16 v[90:91], v197 offset:28160
	v_mfma_f32_32x32x16_bf16 v[68:83], v[164:167], v[128:131], v[68:83]
	v_add_f32_e32 v112, v94, v112
	v_add_f32_e32 v112, v95, v112
	v_cvt_pk_bf16_f32 v136, v92, v93
	v_add_f32_e32 v112, v96, v112
	v_cvt_pk_bf16_f32 v137, v94, v95
	v_add_f32_e32 v112, v97, v112
	ds_read_b64_tr_b16 v[92:93], v197 offset:31744
	ds_read_b64_tr_b16 v[94:95], v197 offset:32256
	v_mfma_f32_32x32x16_bf16 v[52:67], v[160:163], v[128:131], v[52:67]
	v_add_f32_e32 v112, v98, v112
	v_cvt_pk_bf16_f32 v138, v96, v97
	v_add_f32_e32 v112, v99, v112
	v_cvt_pk_bf16_f32 v139, v98, v99
	v_add_f32_e32 v220, v204, v112
	s_add_i32 s10, s24, s46
	s_mov_b32 m0, s10
	s_nop 0
	global_load_lds_dwordx4 v[194:195], off
	s_add_i32 s10, s54, s47
	s_mov_b32 m0, s10
	s_nop 0
	global_load_lds_dwordx4 v[192:193], off
.LBB0_802:
	s_waitcnt lgkmcnt(14)
	v_mfma_f32_32x32x16_bf16 v[20:35], v[148:151], v[152:155], v[20:35]
	v_exp_f32_e32 v68, v68
	v_exp_f32_e32 v69, v69
	v_exp_f32_e32 v70, v70
	v_exp_f32_e32 v71, v71
	s_waitcnt lgkmcnt(12)
	v_mfma_f32_32x32x16_bf16 v[4:19], v[148:151], v[156:159], v[4:19]
	v_exp_f32_e32 v72, v72
	v_exp_f32_e32 v73, v73
	v_exp_f32_e32 v74, v74
	v_exp_f32_e32 v75, v75
	v_add_u32_e32 v96, s54, v218
	ds_read_b128 v[180:183], v96
	ds_read_b128 v[176:179], v96 offset:512
	s_waitcnt lgkmcnt(12)
	v_mfma_f32_32x32x16_bf16 v[20:35], v[144:147], v[100:103], v[20:35]
	v_exp_f32_e32 v76, v76
	v_exp_f32_e32 v77, v77
	v_exp_f32_e32 v78, v78
	v_exp_f32_e32 v79, v79
	ds_read_b128 v[172:175], v96 offset:2048
	ds_read_b128 v[168:171], v96 offset:2560
	s_waitcnt lgkmcnt(12)
	v_mfma_f32_32x32x16_bf16 v[4:19], v[144:147], v[104:107], v[4:19]
	v_exp_f32_e32 v80, v80
	v_exp_f32_e32 v81, v81
	v_exp_f32_e32 v82, v82
	v_exp_f32_e32 v83, v83
	ds_read_b128 v[164:167], v96 offset:4096
	ds_read_b128 v[160:163], v96 offset:4608
	s_waitcnt lgkmcnt(12)
	v_mfma_f32_32x32x16_bf16 v[20:35], v[140:143], v[108:111], v[20:35]
	v_exp_f32_e32 v52, v52
	v_exp_f32_e32 v53, v53
	v_exp_f32_e32 v54, v54
	v_exp_f32_e32 v55, v55
	ds_read_b128 v[156:159], v96 offset:6144
	ds_read_b128 v[152:155], v96 offset:6656
	s_waitcnt lgkmcnt(12)
	v_mfma_f32_32x32x16_bf16 v[4:19], v[140:143], v[84:87], v[4:19]
	v_exp_f32_e32 v56, v56
	v_exp_f32_e32 v57, v57
	v_exp_f32_e32 v58, v58
	v_exp_f32_e32 v59, v59
	s_waitcnt lgkmcnt(10)
	v_mfma_f32_32x32x16_bf16 v[20:35], v[136:139], v[88:91], v[20:35]
	v_exp_f32_e32 v60, v60
	v_exp_f32_e32 v61, v61
	v_exp_f32_e32 v62, v62
	v_exp_f32_e32 v63, v63
	v_bfe_i32 v196, v132, s101, 1
	v_bfi_b32 v246, v196, v222, v223
	s_waitcnt lgkmcnt(8)
	v_mfma_f32_32x32x16_bf16 v[4:19], v[136:139], v[92:95], v[4:19]
	v_exp_f32_e32 v64, v64
	v_exp_f32_e32 v65, v65
	v_exp_f32_e32 v66, v66
	v_exp_f32_e32 v67, v67
	v_mfma_f32_32x32x16_bf16 v[36:51], v[250:253], v[246:249], 0
	s_add_i32 s101, s101, 1
	s_add_i32 s0, s0, 2
	s_add_i32 s10, s54, 0x2000
	s_cmpk_lg_i32 s54, 0x4000
	s_cselect_b32 s42, s10, 0
	v_lshl_add_u64 v[192:193], v[192:193], 0, s[80:81]
	s_cmp_ge_i32 s0, s1
	v_lshl_add_u64 v[194:195], v[194:195], 0, s[80:81]
	s_cbranch_scc1 .Lattn0_exit
	s_mov_b32 s10, s24
	s_mov_b32 s25, s54
	s_mov_b32 s24, s42
	s_branch .Lattn0_head
.Lattn0_exit:
	s_sub_i32 s100, s101, 2
	v_mov_b32_e32 v246, v222
	v_alignbit_b32 v132, v133, v132, s100
	v_alignbit_b32 v133, v134, v133, s100
	v_alignbit_b32 v134, v135, v134, s100
	v_lshrrev_b32_e32 v135, s100, v135
	v_mfma_f32_32x32x16_bf16 v[36:51], v[250:253], v[246:249], 0
	s_nop 7
	s_nop 3
	s_waitcnt vmcnt(2) lgkmcnt(0)
	s_barrier
	s_branch .LBB0_813
